# r55 layout variant: RWKV unit prologue code shifted by 4 bytes, later code by 8 (code alignment tuning)
# speedup vs baseline: 1.0042x; 1.0042x over previous
.LBB0_536:
	v_ashrrev_i32_e32 v3, 3, v5
	v_cmp_lt_i32_e32 vcc, 23, v3
	s_and_saveexec_b64 s[4:5], vcc
	s_xor_b64 s[4:5], exec, s[4:5]
	v_and_b32_e32 v2, -8, v5
	v_add_u32_e32 v2, 0x940, v2
	s_andn2_saveexec_b64 s[4:5], s[4:5]
	s_cbranch_execz .LBB0_535
	v_lshlrev_b32_e32 v2, 5, v3
	v_and_b32_e32 v3, 56, v5
	s_movk_i32 s6, 0xff00
	v_and_or_b32 v2, v2, s6, v3
	v_add_u32_e32 v2, s24, v2
	v_add_u32_e32 v2, 0x700, v2
	s_branch .LBB0_535
	s_nop 0

.Lrw_prio_skip:
	s_branch .LBB0_577
	s_nop 0
